# hyena item prologue: U short-conv hand-written, conv parameters and all four row pieces with halos requested up front (one wait chain instead of ten)
# speedup vs baseline: 1.0029x; 1.0029x over previous
; DI float bf2f(unsigned v) { return __uint_as_float(v << 16); }
; DI float bflo(unsigned v) { return __uint_as_float(v << 16); }
; DI float bfhi(unsigned v) { return __uint_as_float(v & 0xffff0000u); }
; DI void sconv4(const u16* row, int t4, float w0, float w1, float w2, float bias, float (&o)[4]) {
;   const uint2 v = *(const uint2*)(row + t4);
;   const float x0 = bflo(v.x), x1 = bfhi(v.x), x2 = bflo(v.y), x3 = bfhi(v.y);
;   const float xm = (t4 > 0) ? bf2f(row[t4 - 1]) : 0.f;
;   const float xp = (t4 + 4 < SEQ) ? bf2f(row[t4 + 4]) : 0.f;
;   o[0] = w0 * xm + w1 * x0 + w2 * x1 + bias;
;   o[1] = w0 * x0 + w1 * x1 + w2 * x2 + bias;
;   o[2] = w0 * x1 + w1 * x2 + w2 * x3 + bias;
;   o[3] = w0 * x2 + w1 * x3 + w2 * xp + bias;
; }
; DI void hyena_item(const P& p, int l, int c, char* smem) {
;     ...
;   {
;     const float w0 = cw[c], w1 = cw[1536 + c], w2 = cw[3072 + c], bs = cbias[c];
; #pragma unroll
;     for (int i = 0; i < 4; ++i) {
;       const int q = tid + NT * i;
;       const int bt = q >> 10, t8 = (q & 1023) * 8;
;       const u16* row = p.hyT + (size_t)c * HYP + bt * SEQ;
;       float o0[4], o1[4];
;       sconv4(row, t8, w0, w1, w2, bs, o0);
;       sconv4(row, t8 + 4, w0, w1, w2, bs, o1);
;       uint4 ov;
;       ov.x = pack2(o0[0], o0[1]); ov.y = pack2(o0[2], o0[3]); ov.z = pack2(o1[0], o1[1]); ov.w = pack2(o1[2], o1[3]);
;       *(uint4*)(U + (bt * 64 + (t8 >> 7)) * 136 + (t8 & 127)) = ov;
;     }
;   }
.LBB0_417:
	s_or_b64 exec, exec, s[74:75]
	s_lshl_b64 s[78:79], s[72:73], 2
	s_add_u32 s74, s28, s78
	s_addc_u32 s75, s29, s79
	s_or_b32 s56, s72, 0x600
	s_lshl_b64 s[80:81], s[56:57], 2
	s_add_u32 s80, s28, s80
	s_addc_u32 s81, s29, s81
	s_add_u32 s82, s74, 0x3000
	s_addc_u32 s83, s75, 0
	v_readlane_b32 s73, v248, 28
	s_waitcnt vmcnt(0)
	ds_write_b128 v221, v[0:3] offset:24576
	v_perm_b32 v0, v0, v1, s68
	v_perm_b32 v1, v1, v2, s68
	v_perm_b32 v2, v2, v3, s68
	v_or_b32_sdwa v3, v6, v3 dst_sel:DWORD dst_unused:UNUSED_PAD src0_sel:DWORD src1_sel:WORD_1
	s_add_u32 s84, s73, s78
	v_readlane_b32 s73, v248, 29
	ds_write_b128 v221, v[0:3] offset:57408
	s_addc_u32 s85, s73, s79
	s_mul_i32 s96, s72, 0x8080
	v_ashrrev_i32_e32 v1, 10, v20
	s_mul_hi_u32 s73, s72, 0x8080
	s_add_u32 s86, s36, s96
	v_lshlrev_b32_e32 v6, 13, v1
	v_and_b32_e32 v5, 0x1ff8, v190
	s_addc_u32 s87, s37, s73
	v_ashrrev_i32_e32 v7, 31, v6
	v_lshl_add_u64 v[6:7], v[6:7], 1, s[86:87]
	v_lshlrev_b32_e32 v188, 1, v5
	v_lshl_add_u64 v[10:11], v[6:7], 0, v[188:189]
	global_load_dword v244, v189, s[74:75]
	global_load_dword v245, v189, s[80:81]
	global_load_dword v246, v205, s[74:75]
	global_load_dword v247, v189, s[84:85]
	v_lshlrev_b32_e32 v240, 4, v198
	s_add_u32 s98, s86, 0x2000
	s_addc_u32 s99, s87, 0
	s_add_u32 s100, s86, 0x4000
	s_addc_u32 s101, s87, 0
	s_add_u32 s78, s86, 0x6000
	s_addc_u32 s79, s87, 0
	global_load_dwordx4 v[72:75], v240, s[86:87]
	global_load_dword v88, v240, s[86:87] offset:-4
	global_load_dword v92, v240, s[86:87] offset:16
	global_load_dwordx4 v[76:79], v240, s[98:99]
	global_load_dword v89, v240, s[98:99] offset:-4
	global_load_dword v93, v240, s[98:99] offset:16
	global_load_dwordx4 v[80:83], v240, s[100:101]
	global_load_dword v90, v240, s[100:101] offset:-4
	global_load_dword v94, v240, s[100:101] offset:16
	global_load_dwordx4 v[84:87], v240, s[78:79]
	global_load_dword v91, v240, s[78:79] offset:-4
	global_load_dword v95, v240, s[78:79] offset:16
	v_lshrrev_b32_e32 v241, 4, v198
	v_mul_u32_u24_e32 v241, 0x110, v241
	v_and_b32_e32 v242, 15, v198
	v_lshl_add_u32 v241, v242, 4, v241
	v_add_u32_e32 v241, s69, v241
	s_waitcnt vmcnt(9)
	v_cmp_ne_u32_e32 vcc, 0, v198
	v_and_b32_e32 v96, 0xffff0000, v88
	v_lshlrev_b32_e32 v97, 16, v72
	v_and_b32_e32 v98, 0xffff0000, v72
	v_lshlrev_b32_e32 v99, 16, v73
	v_and_b32_e32 v100, 0xffff0000, v73
	v_lshlrev_b32_e32 v101, 16, v74
	v_and_b32_e32 v102, 0xffff0000, v74
	v_lshlrev_b32_e32 v103, 16, v75
	v_and_b32_e32 v104, 0xffff0000, v75
	v_lshlrev_b32_e32 v105, 16, v92
	v_cndmask_b32_e32 v96, 0, v96, vcc
	v_mul_f32_e32 v106, v244, v96
	v_mul_f32_e32 v107, v244, v97
	v_mul_f32_e32 v108, v244, v98
	v_mul_f32_e32 v109, v244, v99
	v_mul_f32_e32 v110, v244, v100
	v_mul_f32_e32 v111, v244, v101
	v_mul_f32_e32 v112, v244, v102
	v_mul_f32_e32 v113, v244, v103
	v_fmac_f32_e32 v106, v245, v97
	v_fmac_f32_e32 v107, v245, v98
	v_fmac_f32_e32 v108, v245, v99
	v_fmac_f32_e32 v109, v245, v100
	v_fmac_f32_e32 v110, v245, v101
	v_fmac_f32_e32 v111, v245, v102
	v_fmac_f32_e32 v112, v245, v103
	v_fmac_f32_e32 v113, v245, v104
	v_fmac_f32_e32 v106, v246, v98
	v_fmac_f32_e32 v107, v246, v99
	v_fmac_f32_e32 v108, v246, v100
	v_fmac_f32_e32 v109, v246, v101
	v_fmac_f32_e32 v110, v246, v102
	v_fmac_f32_e32 v111, v246, v103
	v_fmac_f32_e32 v112, v246, v104
	v_fmac_f32_e32 v113, v246, v105
	v_add_f32_e32 v106, v247, v106
	v_add_f32_e32 v107, v247, v107
	v_add_f32_e32 v108, v247, v108
	v_add_f32_e32 v109, v247, v109
	v_add_f32_e32 v110, v247, v110
	v_add_f32_e32 v111, v247, v111
	v_add_f32_e32 v112, v247, v112
	v_add_f32_e32 v113, v247, v113
	v_cvt_pk_bf16_f32 v114, v106, v107
	v_cvt_pk_bf16_f32 v115, v108, v109
	v_cvt_pk_bf16_f32 v116, v110, v111
	v_cvt_pk_bf16_f32 v117, v112, v113
	ds_write_b128 v241, v[114:117] offset:0
	s_waitcnt vmcnt(6)
	v_cmp_ne_u32_e32 vcc, 0x1ff, v198
	v_and_b32_e32 v96, 0xffff0000, v89
	v_lshlrev_b32_e32 v97, 16, v76
	v_and_b32_e32 v98, 0xffff0000, v76
	v_lshlrev_b32_e32 v99, 16, v77
	v_and_b32_e32 v100, 0xffff0000, v77
	v_lshlrev_b32_e32 v101, 16, v78
	v_and_b32_e32 v102, 0xffff0000, v78
	v_lshlrev_b32_e32 v103, 16, v79
	v_and_b32_e32 v104, 0xffff0000, v79
	v_lshlrev_b32_e32 v105, 16, v93
	v_cndmask_b32_e32 v105, 0, v105, vcc
	v_mul_f32_e32 v106, v244, v96
	v_mul_f32_e32 v107, v244, v97
	v_mul_f32_e32 v108, v244, v98
	v_mul_f32_e32 v109, v244, v99
	v_mul_f32_e32 v110, v244, v100
	v_mul_f32_e32 v111, v244, v101
	v_mul_f32_e32 v112, v244, v102
	v_mul_f32_e32 v113, v244, v103
	v_fmac_f32_e32 v106, v245, v97
	v_fmac_f32_e32 v107, v245, v98
	v_fmac_f32_e32 v108, v245, v99
	v_fmac_f32_e32 v109, v245, v100
	v_fmac_f32_e32 v110, v245, v101
	v_fmac_f32_e32 v111, v245, v102
	v_fmac_f32_e32 v112, v245, v103
	v_fmac_f32_e32 v113, v245, v104
	v_fmac_f32_e32 v106, v246, v98
	v_fmac_f32_e32 v107, v246, v99
	v_fmac_f32_e32 v108, v246, v100
	v_fmac_f32_e32 v109, v246, v101
	v_fmac_f32_e32 v110, v246, v102
	v_fmac_f32_e32 v111, v246, v103
	v_fmac_f32_e32 v112, v246, v104
	v_fmac_f32_e32 v113, v246, v105
	v_add_f32_e32 v106, v247, v106
	v_add_f32_e32 v107, v247, v107
	v_add_f32_e32 v108, v247, v108
	v_add_f32_e32 v109, v247, v109
	v_add_f32_e32 v110, v247, v110
	v_add_f32_e32 v111, v247, v111
	v_add_f32_e32 v112, v247, v112
	v_add_f32_e32 v113, v247, v113
	v_cvt_pk_bf16_f32 v114, v106, v107
	v_cvt_pk_bf16_f32 v115, v108, v109
	v_cvt_pk_bf16_f32 v116, v110, v111
	v_cvt_pk_bf16_f32 v117, v112, v113
	ds_write_b128 v241, v[114:117] offset:8704
	s_waitcnt vmcnt(3)
; DI void hyena_item(const P& p, int l, int c, char* smem) {
;     ...
; #pragma unroll
;     for (int i = 0; i < 4; ++i) {
;       const int q = tid + NT * i;
;       const int bt = q >> 10, t8 = (q & 1023) * 8;
;       const u16* row = p.hyT + (size_t)c * HYP + bt * SEQ;
;       float o0[4], o1[4];
;       sconv4(row, t8, w0, w1, w2, bs, o0);
;       sconv4(row, t8 + 4, w0, w1, w2, bs, o1);
;       uint4 ov;
;       ov.x = pack2(o0[0], o0[1]); ov.y = pack2(o0[2], o0[3]); ov.z = pack2(o1[0], o1[1]); ov.w = pack2(o1[2], o1[3]);
;       *(uint4*)(U + (bt * 64 + (t8 >> 7)) * 136 + (t8 & 127)) = ov;
;     }
;   }
;   __syncthreads();
;   const float invn0 = 1.0f / (misc[4] + misc[5] + misc[6] + misc[7]);
;   const float invn1 = 1.0f / (misc[8] + misc[9] + misc[10] + misc[11]);
;   const u16* abase = (li & 1) ? (TbO + (8192 - li + 8 * g - 1)) : (TbE + (8192 - li + 8 * g));
;   const int bt = li >> 4;
;   const int a = a0 + (li & 15);
;   f32x16 acc[4];
;   if (cwv) hy_conv(acc, abase, U, Zrow, a0, li, g);
;   __syncthreads();
	v_cmp_ne_u32_e32 vcc, 0, v198
	v_and_b32_e32 v96, 0xffff0000, v90
	v_lshlrev_b32_e32 v97, 16, v80
	v_and_b32_e32 v98, 0xffff0000, v80
	v_lshlrev_b32_e32 v99, 16, v81
	v_and_b32_e32 v100, 0xffff0000, v81
	v_lshlrev_b32_e32 v101, 16, v82
	v_and_b32_e32 v102, 0xffff0000, v82
	v_lshlrev_b32_e32 v103, 16, v83
	v_and_b32_e32 v104, 0xffff0000, v83
	v_lshlrev_b32_e32 v105, 16, v94
	v_cndmask_b32_e32 v96, 0, v96, vcc
	v_mul_f32_e32 v106, v244, v96
	v_mul_f32_e32 v107, v244, v97
	v_mul_f32_e32 v108, v244, v98
	v_mul_f32_e32 v109, v244, v99
	v_mul_f32_e32 v110, v244, v100
	v_mul_f32_e32 v111, v244, v101
	v_mul_f32_e32 v112, v244, v102
	v_mul_f32_e32 v113, v244, v103
	v_fmac_f32_e32 v106, v245, v97
	v_fmac_f32_e32 v107, v245, v98
	v_fmac_f32_e32 v108, v245, v99
	v_fmac_f32_e32 v109, v245, v100
	v_fmac_f32_e32 v110, v245, v101
	v_fmac_f32_e32 v111, v245, v102
	v_fmac_f32_e32 v112, v245, v103
	v_fmac_f32_e32 v113, v245, v104
	v_fmac_f32_e32 v106, v246, v98
	v_fmac_f32_e32 v107, v246, v99
	v_fmac_f32_e32 v108, v246, v100
	v_fmac_f32_e32 v109, v246, v101
	v_fmac_f32_e32 v110, v246, v102
	v_fmac_f32_e32 v111, v246, v103
	v_fmac_f32_e32 v112, v246, v104
	v_fmac_f32_e32 v113, v246, v105
	v_add_f32_e32 v106, v247, v106
	v_add_f32_e32 v107, v247, v107
	v_add_f32_e32 v108, v247, v108
	v_add_f32_e32 v109, v247, v109
	v_add_f32_e32 v110, v247, v110
	v_add_f32_e32 v111, v247, v111
	v_add_f32_e32 v112, v247, v112
	v_add_f32_e32 v113, v247, v113
	v_cvt_pk_bf16_f32 v114, v106, v107
	v_cvt_pk_bf16_f32 v115, v108, v109
	v_cvt_pk_bf16_f32 v116, v110, v111
	v_cvt_pk_bf16_f32 v117, v112, v113
	ds_write_b128 v241, v[114:117] offset:17408
	s_waitcnt vmcnt(0)
	v_cmp_ne_u32_e32 vcc, 0x1ff, v198
	v_and_b32_e32 v96, 0xffff0000, v91
	v_lshlrev_b32_e32 v97, 16, v84
	v_and_b32_e32 v98, 0xffff0000, v84
	v_lshlrev_b32_e32 v99, 16, v85
	v_and_b32_e32 v100, 0xffff0000, v85
	v_lshlrev_b32_e32 v101, 16, v86
	v_and_b32_e32 v102, 0xffff0000, v86
	v_lshlrev_b32_e32 v103, 16, v87
	v_and_b32_e32 v104, 0xffff0000, v87
	v_lshlrev_b32_e32 v105, 16, v95
	v_cndmask_b32_e32 v105, 0, v105, vcc
	v_mul_f32_e32 v106, v244, v96
	v_mul_f32_e32 v107, v244, v97
	v_mul_f32_e32 v108, v244, v98
	v_mul_f32_e32 v109, v244, v99
	v_mul_f32_e32 v110, v244, v100
	v_mul_f32_e32 v111, v244, v101
	v_mul_f32_e32 v112, v244, v102
	v_mul_f32_e32 v113, v244, v103
	v_fmac_f32_e32 v106, v245, v97
	v_fmac_f32_e32 v107, v245, v98
	v_fmac_f32_e32 v108, v245, v99
	v_fmac_f32_e32 v109, v245, v100
	v_fmac_f32_e32 v110, v245, v101
	v_fmac_f32_e32 v111, v245, v102
	v_fmac_f32_e32 v112, v245, v103
	v_fmac_f32_e32 v113, v245, v104
	v_fmac_f32_e32 v106, v246, v98
	v_fmac_f32_e32 v107, v246, v99
	v_fmac_f32_e32 v108, v246, v100
	v_fmac_f32_e32 v109, v246, v101
	v_fmac_f32_e32 v110, v246, v102
	v_fmac_f32_e32 v111, v246, v103
	v_fmac_f32_e32 v112, v246, v104
	v_fmac_f32_e32 v113, v246, v105
	v_add_f32_e32 v106, v247, v106
	v_add_f32_e32 v107, v247, v107
	v_add_f32_e32 v108, v247, v108
	v_add_f32_e32 v109, v247, v109
	v_add_f32_e32 v110, v247, v110
	v_add_f32_e32 v111, v247, v111
	v_add_f32_e32 v112, v247, v112
	v_add_f32_e32 v113, v247, v113
	v_cvt_pk_bf16_f32 v114, v106, v107
	v_cvt_pk_bf16_f32 v115, v108, v109
	v_cvt_pk_bf16_f32 v116, v110, v111
	v_cvt_pk_bf16_f32 v117, v112, v113
	ds_write_b128 v241, v[114:117] offset:26112
	v_readlane_b32 s78, v248, 10
	s_nop 1
	v_mov_b32_e32 v0, s78
	v_readlane_b32 s78, v248, 11
	v_lshrrev_b32_e32 v188, 5, v21
	v_and_b32_e32 v230, 31, v20
	v_mov_b32_e32 v1, s78
	s_waitcnt lgkmcnt(0)
	s_barrier
	ds_read_b128 v[68:71], v0
	ds_read_b128 v[64:67], v1
	v_and_b32_e32 v0, 1, v20
	v_lshlrev_b32_e32 v1, 3, v188
	v_readlane_b32 s78, v248, 12
	v_sub_u32_e32 v1, v1, v230
	v_cmp_eq_u32_e32 vcc, 0, v0
	v_mov_b32_e32 v3, s78
	v_lshlrev_b32_e32 v2, 4, v22
	v_cndmask_b32_e64 v0, v3, 0, vcc
	v_cndmask_b32_e32 v3, v217, v207, vcc
	v_lshlrev_b32_e32 v1, 1, v1
	v_and_b32_e32 v231, 48, v2
	v_add3_u32 v225, v0, v1, v3
	v_and_b32_e32 v223, 15, v20
	v_lshlrev_b32_e32 v0, 2, v230
	v_or_b32_e32 v226, 15, v231
	v_lshlrev_b32_e32 v222, 4, v188
	v_or_b32_e32 v227, 14, v231
	v_add_u32_e32 v229, v231, v223
	v_or_b32_e32 v228, 0xffffffc1, v2
	v_and_b32_e32 v224, 64, v0
	v_mov_b32_e32 v250, 40
	v_cndmask_b32_e64 v249, v250, 0, s[6:7]
	v_add_u32_e32 v228, v228, v249
	v_mov_b32_e32 v250, 39
	v_cndmask_b32_e64 v249, 0, v250, s[6:7]
	v_sub_u32_e32 v227, v227, v249
	v_mov_b32_e32 v249, 24
	v_mov_b32_e32 v250, -15
	v_cndmask_b32_e64 v250, v250, v249, s[6:7]
	s_and_b64 vcc, exec, s[6:7]
	s_cbranch_vccnz .Lhy_pf_skip
	s_or_b32 s78, s72, 0x200
	s_mul_hi_u32 s79, s78, 0x8080
	s_mul_i32 s78, s78, 0x8080
	s_add_u32 s78, s36, s78
	s_addc_u32 s79, s37, s79
	v_and_b32_e32 v240, 0xff, v198
	v_lshlrev_b32_e32 v240, 7, v240
	global_load_dword v251, v240, s[78:79]
	s_add_u32 s78, s78, 0x1010000
	s_addc_u32 s79, s79, 0
	global_load_dword v251, v240, s[78:79]
	s_add_u32 s78, s78, 0x1010000
	s_addc_u32 s79, s79, 0
	global_load_dword v251, v240, s[78:79]
